# grid barrier acquire: XCD leader waits for its L2 invalidate before releasing; released workgroups invalidate L1 only (buffer_inv sc0)
# speedup vs baseline: 1.0109x; 1.0109x over previous
.LBB0_1513:
	s_or_b64 exec, exec, s[4:5]
	s_waitcnt vmcnt(0)
	buffer_inv sc0
	s_waitcnt vmcnt(0)

.LBB0_1531:
	s_or_b64 exec, exec, s[2:3]
	s_mov_b64 s[2:3], exec
	v_mbcnt_lo_u32_b32 v1, s2, 0
	v_mbcnt_hi_u32_b32 v1, s3, v1
	v_cmp_eq_u32_e32 vcc, 0, v1
	s_waitcnt vmcnt(0)
	buffer_inv sc1
	s_and_saveexec_b64 s[4:5], vcc
	s_cbranch_execz .LBB0_1533
	s_bcnt1_i32_b64 s2, s[2:3]
	v_mov_b32_e32 v1, s2
	v_readlane_b32 s2, v254, 62
	v_readlane_b32 s3, v254, 63
	s_branch .Lxinv
.Lxinv_ret:
	global_atomic_add v0, v1, s[2:3]

.Lxinv:
	s_waitcnt vmcnt(0)
	s_nop 4
	s_branch .Lxinv_ret
